# GEMM phase cold start: idle waves touch the first two k-slabs of the next phase's weight rows (1/32 share per workgroup) while thread 0 runs the preceding grid barrier, seven GEMM phase starts; on top
# baseline (speedup 1.0000x reference)
; __device__ __forceinline__ unsigned xb_ld(unsigned* p)              { return __hip_atomic_load(p, __ATOMIC_RELAXED, __HIP_MEMORY_SCOPE_AGENT); }
; __device__ __forceinline__ unsigned xb_add(unsigned* p, unsigned v) { return __hip_atomic_fetch_add(p, v, __ATOMIC_RELAXED, __HIP_MEMORY_SCOPE_AGENT); }
; #define XB_SPIN(cond, bar) do { unsigned _sp = 0; while (cond) { __builtin_amdgcn_s_sleep(1); \
;     if ((++_sp & 255u) == 0u) { if (xb_ld(&(bar)[XB_TMO])) break; if (_sp > XB_SPIN_CAP) { atomicAdd(&(bar)[XB_TMO], 1u); break; } } } } while (0)
; __device__ __forceinline__ void xcd_barrier(const XcdBarrier& b) {
;     asm volatile("s_waitcnt vmcnt(0)" ::: "memory");
;     __syncthreads();
;     if (threadIdx.x == 0) {
;         unsigned* bar = b.bar;
;         __builtin_amdgcn_s_waitcnt(0);
;         unsigned nloc = b.st[0], nx = b.st[1];
;         if (nloc == 0u) { xcd_barrier_complete(bar, b.x, nloc, nx); b.st[0] = nloc; b.st[1] = nx; }
;         const unsigned old = xb_add(&bar[XB_XSUB(b.x)], 1u);
;         const unsigned gen = old / nloc;
;         if (old + 1u == (gen + 1u) * nloc) {
;             __builtin_amdgcn_fence(__ATOMIC_RELEASE, "agent");
;             asm volatile("s_waitcnt vmcnt(0)" ::: "memory");
;             const unsigned og = xb_add(&bar[XB_TOP], 1u);
;             const unsigned tg = og / nx;
;             if (og + 1u == (tg + 1u) * nx) xb_add(&bar[XB_TOPGEN], 1u);
;             else XB_SPIN(xb_ld(&bar[XB_TOPGEN]) == tg, bar);
;             __builtin_amdgcn_fence(__ATOMIC_ACQUIRE, "agent");
;             xb_add(&bar[XB_XGEN(b.x)], 1u);
;             asm volatile("s_waitcnt vmcnt(0)" ::: "memory");
;         } else {
;             XB_SPIN(xb_ld(&bar[XB_XGEN(b.x)]) == gen, bar);
;             __builtin_amdgcn_fence(__ATOMIC_ACQUIRE, "agent");
;             asm volatile("s_waitcnt vmcnt(0)" ::: "memory");
;         }
;     }
;     __syncthreads();
; }
.LBB0_188:
	s_waitcnt vmcnt(0)
	s_barrier
	s_cmp_lg_u64 s[92:93], 0
	s_cbranch_scc1 .Lbw_p1
	v_readlane_b32 s98, v238, 40
	s_nop 3
	s_cmp_gt_u32 s98, 6
	s_cbranch_scc1 .Lbw_p1
	v_mbcnt_lo_u32_b32 v235, -1, 0
	v_mbcnt_hi_u32_b32 v235, -1, v235
	s_add_i32 s98, s98, -1
	s_lshl_b32 s98, s98, 6
	v_add_u32_e32 v235, s98, v235
	s_lshr_b32 s99, s20, 3
	s_mul_i32 s99, s99, 0x58000
	v_lshrrev_b32_e32 v236, 1, v235
	v_and_b32_e32 v235, 1, v235
	v_min_u32_e32 v236, 175, v236
	v_mul_u32_u24_e32 v236, 0x800, v236
	v_lshl_or_b32 v236, v235, 7, v236
	v_add_u32_e32 v236, s99, v236
	s_add_u32 s100, s30, 0x100000
	s_addc_u32 s101, s31, 0
	global_load_dword v237, v236, s[100:101]
.Lbw_p1:
	s_and_saveexec_b64 s[0:1], s[92:93]
	s_cbranch_execz .LBB0_240
	s_add_i32 s8, 0, 0x23fe0
	v_mov_b32_e32 v0, s8
	s_waitcnt vmcnt(0) expcnt(0) lgkmcnt(0)
	ds_read_b32 v2, v0
	s_add_i32 s8, 0, 0x23fe4
	v_mov_b32_e32 v0, s8
	ds_read_b32 v0, v0
	s_waitcnt lgkmcnt(1)
	v_cmp_ne_u32_e32 vcc, 0, v2
	s_cbranch_vccnz .LBB0_204
	s_add_u32 s8, s30, 0x1000
	s_addc_u32 s9, s31, 0
	s_add_u32 s10, s30, 0x1100
	s_addc_u32 s11, s31, 0
	s_add_u32 s12, s30, 0x1200
	s_addc_u32 s13, s31, 0
	s_mul_i32 s18, s91, s85
	s_add_u32 s14, s30, 0x1300
	s_mul_i32 s18, s18, s90
	s_addc_u32 s15, s31, 0
	s_mov_b32 s19, 1
	v_mov_b32_e32 v16, 0
	s_branch .LBB0_192

; __device__ __forceinline__ unsigned xb_ld(unsigned* p)              { return __hip_atomic_load(p, __ATOMIC_RELAXED, __HIP_MEMORY_SCOPE_AGENT); }
; __device__ __forceinline__ unsigned xb_add(unsigned* p, unsigned v) { return __hip_atomic_fetch_add(p, v, __ATOMIC_RELAXED, __HIP_MEMORY_SCOPE_AGENT); }
; #define XB_SPIN(cond, bar) do { unsigned _sp = 0; while (cond) { __builtin_amdgcn_s_sleep(1); \
;     if ((++_sp & 255u) == 0u) { if (xb_ld(&(bar)[XB_TMO])) break; if (_sp > XB_SPIN_CAP) { atomicAdd(&(bar)[XB_TMO], 1u); break; } } } } while (0)
; __device__ __forceinline__ void xcd_barrier(const XcdBarrier& b) {
;     asm volatile("s_waitcnt vmcnt(0)" ::: "memory");
;     __syncthreads();
;     if (threadIdx.x == 0) {
;         unsigned* bar = b.bar;
;         __builtin_amdgcn_s_waitcnt(0);
;         unsigned nloc = b.st[0], nx = b.st[1];
;         if (nloc == 0u) { xcd_barrier_complete(bar, b.x, nloc, nx); b.st[0] = nloc; b.st[1] = nx; }
;         const unsigned old = xb_add(&bar[XB_XSUB(b.x)], 1u);
;         const unsigned gen = old / nloc;
;         if (old + 1u == (gen + 1u) * nloc) {
;             __builtin_amdgcn_fence(__ATOMIC_RELEASE, "agent");
;             asm volatile("s_waitcnt vmcnt(0)" ::: "memory");
;             const unsigned og = xb_add(&bar[XB_TOP], 1u);
;             const unsigned tg = og / nx;
;             if (og + 1u == (tg + 1u) * nx) xb_add(&bar[XB_TOPGEN], 1u);
;             else XB_SPIN(xb_ld(&bar[XB_TOPGEN]) == tg, bar);
;             __builtin_amdgcn_fence(__ATOMIC_ACQUIRE, "agent");
;             xb_add(&bar[XB_XGEN(b.x)], 1u);
;             asm volatile("s_waitcnt vmcnt(0)" ::: "memory");
;         } else {
;             XB_SPIN(xb_ld(&bar[XB_XGEN(b.x)]) == gen, bar);
;             __builtin_amdgcn_fence(__ATOMIC_ACQUIRE, "agent");
;             asm volatile("s_waitcnt vmcnt(0)" ::: "memory");
;         }
;     }
;     __syncthreads();
; }
.LBB0_289:
	s_waitcnt vmcnt(0)
	s_waitcnt vmcnt(0)
	s_barrier
	s_cmp_lg_u64 s[92:93], 0
	s_cbranch_scc1 .Lbw_p2
	v_readlane_b32 s98, v238, 40
	s_nop 3
	s_cmp_gt_u32 s98, 1
	s_cbranch_scc1 .Lbw_p2
	v_mbcnt_lo_u32_b32 v235, -1, 0
	v_mbcnt_hi_u32_b32 v235, -1, v235
	s_add_i32 s98, s98, -1
	s_lshl_b32 s98, s98, 6
	v_add_u32_e32 v235, s98, v235
	s_lshr_b32 s99, s20, 3
	s_mul_i32 s99, s99, 0x2c000
	v_lshrrev_b32_e32 v236, 1, v235
	v_and_b32_e32 v235, 1, v235
	v_min_u32_e32 v236, 31, v236
	v_mul_u32_u24_e32 v236, 0x1600, v236
	v_lshl_or_b32 v236, v235, 7, v236
	v_add_u32_e32 v236, s99, v236
	s_add_u32 s100, s30, 0xc00000
	s_addc_u32 s101, s31, 0
	global_load_dword v237, v236, s[100:101]
.Lbw_p2:
	s_and_saveexec_b64 s[0:1], s[92:93]
	s_cbranch_execz .LBB0_341
	s_add_i32 s4, 0, 0x23fe0
	v_mov_b32_e32 v0, s4
	s_waitcnt vmcnt(0) expcnt(0) lgkmcnt(0)
	ds_read_b32 v2, v0
	s_add_i32 s4, 0, 0x23fe4
	v_mov_b32_e32 v0, s4
	ds_read_b32 v0, v0
	s_waitcnt lgkmcnt(1)
	v_cmp_ne_u32_e32 vcc, 0, v2
	s_cbranch_vccnz .LBB0_305
	s_add_u32 s4, s30, 0x1000
	s_addc_u32 s5, s31, 0
	s_add_u32 s10, s30, 0x1100
	s_addc_u32 s11, s31, 0
	s_add_u32 s12, s30, 0x1200
	s_addc_u32 s13, s31, 0
	s_mul_i32 s18, s91, s85
	s_add_u32 s14, s30, 0x1300
	s_mul_i32 s18, s18, s90
	s_addc_u32 s15, s31, 0
	s_mov_b32 s19, 1
	v_mov_b32_e32 v16, 0
	s_branch .LBB0_293

; __device__ __forceinline__ unsigned xb_ld(unsigned* p)              { return __hip_atomic_load(p, __ATOMIC_RELAXED, __HIP_MEMORY_SCOPE_AGENT); }
; __device__ __forceinline__ unsigned xb_add(unsigned* p, unsigned v) { return __hip_atomic_fetch_add(p, v, __ATOMIC_RELAXED, __HIP_MEMORY_SCOPE_AGENT); }
; #define XB_SPIN(cond, bar) do { unsigned _sp = 0; while (cond) { __builtin_amdgcn_s_sleep(1); \
;     if ((++_sp & 255u) == 0u) { if (xb_ld(&(bar)[XB_TMO])) break; if (_sp > XB_SPIN_CAP) { atomicAdd(&(bar)[XB_TMO], 1u); break; } } } } while (0)
; __device__ __forceinline__ void xcd_barrier(const XcdBarrier& b) {
;     asm volatile("s_waitcnt vmcnt(0)" ::: "memory");
;     __syncthreads();
;     if (threadIdx.x == 0) {
;         unsigned* bar = b.bar;
;         __builtin_amdgcn_s_waitcnt(0);
;         unsigned nloc = b.st[0], nx = b.st[1];
;         if (nloc == 0u) { xcd_barrier_complete(bar, b.x, nloc, nx); b.st[0] = nloc; b.st[1] = nx; }
;         const unsigned old = xb_add(&bar[XB_XSUB(b.x)], 1u);
;         const unsigned gen = old / nloc;
;         if (old + 1u == (gen + 1u) * nloc) {
;             __builtin_amdgcn_fence(__ATOMIC_RELEASE, "agent");
;             asm volatile("s_waitcnt vmcnt(0)" ::: "memory");
;             const unsigned og = xb_add(&bar[XB_TOP], 1u);
;             const unsigned tg = og / nx;
;             if (og + 1u == (tg + 1u) * nx) xb_add(&bar[XB_TOPGEN], 1u);
;             else XB_SPIN(xb_ld(&bar[XB_TOPGEN]) == tg, bar);
;             __builtin_amdgcn_fence(__ATOMIC_ACQUIRE, "agent");
;             xb_add(&bar[XB_XGEN(b.x)], 1u);
;             asm volatile("s_waitcnt vmcnt(0)" ::: "memory");
;         } else {
;             XB_SPIN(xb_ld(&bar[XB_XGEN(b.x)]) == gen, bar);
;             __builtin_amdgcn_fence(__ATOMIC_ACQUIRE, "agent");
;             asm volatile("s_waitcnt vmcnt(0)" ::: "memory");
;         }
;     }
;     __syncthreads();
; }
.LBB0_745:
	s_waitcnt vmcnt(0)
	s_barrier
	s_cmp_lg_u64 s[92:93], 0
	s_cbranch_scc1 .Lbw_p4c
	v_readlane_b32 s98, v238, 40
	s_nop 3
	s_cmp_gt_u32 s98, 5
	s_cbranch_scc1 .Lbw_p4c
	v_mbcnt_lo_u32_b32 v235, -1, 0
	v_mbcnt_hi_u32_b32 v235, -1, v235
	s_add_i32 s98, s98, -1
	s_lshl_b32 s98, s98, 6
	v_add_u32_e32 v235, s98, v235
	s_lshr_b32 s99, s20, 3
	s_mul_i32 s99, s99, 0x50000
	v_lshrrev_b32_e32 v236, 1, v235
	v_and_b32_e32 v235, 1, v235
	v_min_u32_e32 v236, 159, v236
	v_mul_u32_u24_e32 v236, 0x800, v236
	v_lshl_or_b32 v236, v235, 7, v236
	v_add_u32_e32 v236, s99, v236
	s_add_u32 s100, s30, 0x2900000
	s_addc_u32 s101, s31, 0
	global_load_dword v237, v236, s[100:101]
.Lbw_p4c:
	s_and_saveexec_b64 s[0:1], s[92:93]
	s_cbranch_execz .LBB0_797
	s_add_i32 s2, 0, 0x23fe0
	v_mov_b32_e32 v0, s2
	s_waitcnt vmcnt(0) expcnt(0) lgkmcnt(0)
	ds_read_b32 v2, v0
	s_add_i32 s2, 0, 0x23fe4
	v_mov_b32_e32 v0, s2
	ds_read_b32 v0, v0
	s_waitcnt lgkmcnt(1)
	v_cmp_ne_u32_e32 vcc, 0, v2
	s_cbranch_vccnz .LBB0_761
	s_add_u32 s4, s30, 0x1000
	s_addc_u32 s5, s31, 0
	s_add_u32 s6, s30, 0x1100
	s_addc_u32 s7, s31, 0
	s_add_u32 s8, s30, 0x1200
	s_addc_u32 s9, s31, 0
	s_mul_i32 s2, s91, s85
	s_add_u32 s10, s30, 0x1300
	s_mul_i32 s2, s2, s90
	s_addc_u32 s11, s31, 0
	s_mov_b32 s16, 1
	v_mov_b32_e32 v16, 0
	s_branch .LBB0_749

; __device__ __forceinline__ unsigned xb_ld(unsigned* p)              { return __hip_atomic_load(p, __ATOMIC_RELAXED, __HIP_MEMORY_SCOPE_AGENT); }
; __device__ __forceinline__ unsigned xb_add(unsigned* p, unsigned v) { return __hip_atomic_fetch_add(p, v, __ATOMIC_RELAXED, __HIP_MEMORY_SCOPE_AGENT); }
; #define XB_SPIN(cond, bar) do { unsigned _sp = 0; while (cond) { __builtin_amdgcn_s_sleep(1); \
;     if ((++_sp & 255u) == 0u) { if (xb_ld(&(bar)[XB_TMO])) break; if (_sp > XB_SPIN_CAP) { atomicAdd(&(bar)[XB_TMO], 1u); break; } } } } while (0)
; __device__ __forceinline__ void xcd_barrier(const XcdBarrier& b) {
;     asm volatile("s_waitcnt vmcnt(0)" ::: "memory");
;     __syncthreads();
;     if (threadIdx.x == 0) {
;         unsigned* bar = b.bar;
;         __builtin_amdgcn_s_waitcnt(0);
;         unsigned nloc = b.st[0], nx = b.st[1];
;         if (nloc == 0u) { xcd_barrier_complete(bar, b.x, nloc, nx); b.st[0] = nloc; b.st[1] = nx; }
;         const unsigned old = xb_add(&bar[XB_XSUB(b.x)], 1u);
;         const unsigned gen = old / nloc;
;         if (old + 1u == (gen + 1u) * nloc) {
;             __builtin_amdgcn_fence(__ATOMIC_RELEASE, "agent");
;             asm volatile("s_waitcnt vmcnt(0)" ::: "memory");
;             const unsigned og = xb_add(&bar[XB_TOP], 1u);
;             const unsigned tg = og / nx;
;             if (og + 1u == (tg + 1u) * nx) xb_add(&bar[XB_TOPGEN], 1u);
;             else XB_SPIN(xb_ld(&bar[XB_TOPGEN]) == tg, bar);
;             __builtin_amdgcn_fence(__ATOMIC_ACQUIRE, "agent");
;             xb_add(&bar[XB_XGEN(b.x)], 1u);
;             asm volatile("s_waitcnt vmcnt(0)" ::: "memory");
;         } else {
;             XB_SPIN(xb_ld(&bar[XB_XGEN(b.x)]) == gen, bar);
;             __builtin_amdgcn_fence(__ATOMIC_ACQUIRE, "agent");
;             asm volatile("s_waitcnt vmcnt(0)" ::: "memory");
;         }
;     }
;     __syncthreads();
; }
.LBB0_943:
	s_waitcnt vmcnt(0)
	s_barrier
	s_cmp_lg_u64 s[92:93], 0
	s_cbranch_scc1 .Lbw_p7a
	v_readlane_b32 s98, v238, 40
	s_nop 3
	s_cmp_gt_u32 s98, 1
	s_cbranch_scc1 .Lbw_p7a
	v_mbcnt_lo_u32_b32 v235, -1, 0
	v_mbcnt_hi_u32_b32 v235, -1, v235
	s_add_i32 s98, s98, -1
	s_lshl_b32 s98, s98, 6
	v_add_u32_e32 v235, s98, v235
	s_lshr_b32 s99, s20, 3
	s_mul_i32 s99, s99, 0x10000
	v_lshrrev_b32_e32 v236, 1, v235
	v_and_b32_e32 v235, 1, v235
	v_min_u32_e32 v236, 31, v236
	v_mul_u32_u24_e32 v236, 0x800, v236
	v_lshl_or_b32 v236, v235, 7, v236
	v_add_u32_e32 v236, s99, v236
	s_add_u32 s100, s30, 0x3300000
	s_addc_u32 s101, s31, 0
	global_load_dword v237, v236, s[100:101]

; __device__ __forceinline__ unsigned xb_ld(unsigned* p)              { return __hip_atomic_load(p, __ATOMIC_RELAXED, __HIP_MEMORY_SCOPE_AGENT); }
; __device__ __forceinline__ unsigned xb_add(unsigned* p, unsigned v) { return __hip_atomic_fetch_add(p, v, __ATOMIC_RELAXED, __HIP_MEMORY_SCOPE_AGENT); }
; #define XB_SPIN(cond, bar) do { unsigned _sp = 0; while (cond) { __builtin_amdgcn_s_sleep(1); \
;     if ((++_sp & 255u) == 0u) { if (xb_ld(&(bar)[XB_TMO])) break; if (_sp > XB_SPIN_CAP) { atomicAdd(&(bar)[XB_TMO], 1u); break; } } } } while (0)
; __device__ __forceinline__ void xcd_barrier(const XcdBarrier& b) {
;     asm volatile("s_waitcnt vmcnt(0)" ::: "memory");
;     __syncthreads();
;     if (threadIdx.x == 0) {
;         unsigned* bar = b.bar;
;         __builtin_amdgcn_s_waitcnt(0);
;         unsigned nloc = b.st[0], nx = b.st[1];
;         if (nloc == 0u) { xcd_barrier_complete(bar, b.x, nloc, nx); b.st[0] = nloc; b.st[1] = nx; }
;         const unsigned old = xb_add(&bar[XB_XSUB(b.x)], 1u);
;         const unsigned gen = old / nloc;
;         if (old + 1u == (gen + 1u) * nloc) {
;             __builtin_amdgcn_fence(__ATOMIC_RELEASE, "agent");
;             asm volatile("s_waitcnt vmcnt(0)" ::: "memory");
;             const unsigned og = xb_add(&bar[XB_TOP], 1u);
;             const unsigned tg = og / nx;
;             if (og + 1u == (tg + 1u) * nx) xb_add(&bar[XB_TOPGEN], 1u);
;             else XB_SPIN(xb_ld(&bar[XB_TOPGEN]) == tg, bar);
;             __builtin_amdgcn_fence(__ATOMIC_ACQUIRE, "agent");
;             xb_add(&bar[XB_XGEN(b.x)], 1u);
;             asm volatile("s_waitcnt vmcnt(0)" ::: "memory");
;         } else {
;             XB_SPIN(xb_ld(&bar[XB_XGEN(b.x)]) == gen, bar);
;             __builtin_amdgcn_fence(__ATOMIC_ACQUIRE, "agent");
;             asm volatile("s_waitcnt vmcnt(0)" ::: "memory");
;         }
;     }
;     __syncthreads();
; }
.LBB0_1044:
	s_waitcnt vmcnt(0)
	s_barrier
	s_cmp_lg_u64 s[92:93], 0
	s_cbranch_scc1 .Lbw_p8
	v_readlane_b32 s98, v238, 40
	s_nop 3
	s_cmp_gt_u32 s98, 1
	s_cbranch_scc1 .Lbw_p8
	v_mbcnt_lo_u32_b32 v235, -1, 0
	v_mbcnt_hi_u32_b32 v235, -1, v235
	s_add_i32 s98, s98, -1
	s_lshl_b32 s98, s98, 6
	v_add_u32_e32 v235, s98, v235
	s_lshr_b32 s99, s20, 3
	s_mul_i32 s99, s99, 0x10000
	v_lshrrev_b32_e32 v236, 1, v235
	v_and_b32_e32 v235, 1, v235
	v_min_u32_e32 v236, 31, v236
	v_mul_u32_u24_e32 v236, 0x800, v236
	v_lshl_or_b32 v236, v235, 7, v236
	v_add_u32_e32 v236, s99, v236
	s_add_u32 s100, s30, 0x3700000
	s_addc_u32 s101, s31, 0
	global_load_dword v237, v236, s[100:101]
.Lbw_p8:
	s_and_saveexec_b64 s[4:5], s[92:93]
	s_cbranch_execz .LBB0_1096
	s_add_i32 s2, 0, 0x23fe0
	v_mov_b32_e32 v0, s2
	s_waitcnt vmcnt(0) expcnt(0) lgkmcnt(0)
	ds_read_b32 v2, v0
	s_add_i32 s2, 0, 0x23fe4
	v_mov_b32_e32 v0, s2
	ds_read_b32 v0, v0
	s_waitcnt lgkmcnt(1)
	v_cmp_ne_u32_e32 vcc, 0, v2
	s_cbranch_vccnz .LBB0_1060
	s_add_u32 s6, s30, 0x1000
	s_addc_u32 s7, s31, 0
	s_add_u32 s8, s30, 0x1100
	s_addc_u32 s9, s31, 0
	s_add_u32 s10, s30, 0x1200
	s_addc_u32 s11, s31, 0
	s_mul_i32 s2, s91, s85
	s_add_u32 s12, s30, 0x1300
	s_mul_i32 s2, s2, s90
	s_addc_u32 s13, s31, 0
	s_mov_b32 s16, 1
	v_mov_b32_e32 v16, 0
	s_branch .LBB0_1048
.LBB0_1047:
	s_and_b64 vcc, exec, s[44:45]
	s_cbranch_vccnz .LBB0_1055

; __device__ __forceinline__ unsigned xb_ld(unsigned* p)              { return __hip_atomic_load(p, __ATOMIC_RELAXED, __HIP_MEMORY_SCOPE_AGENT); }
; __device__ __forceinline__ unsigned xb_add(unsigned* p, unsigned v) { return __hip_atomic_fetch_add(p, v, __ATOMIC_RELAXED, __HIP_MEMORY_SCOPE_AGENT); }
; #define XB_SPIN(cond, bar) do { unsigned _sp = 0; while (cond) { __builtin_amdgcn_s_sleep(1); \
;     if ((++_sp & 255u) == 0u) { if (xb_ld(&(bar)[XB_TMO])) break; if (_sp > XB_SPIN_CAP) { atomicAdd(&(bar)[XB_TMO], 1u); break; } } } } while (0)
; __device__ __forceinline__ void xcd_barrier(const XcdBarrier& b) {
;     asm volatile("s_waitcnt vmcnt(0)" ::: "memory");
;     __syncthreads();
;     if (threadIdx.x == 0) {
;         unsigned* bar = b.bar;
;         __builtin_amdgcn_s_waitcnt(0);
;         unsigned nloc = b.st[0], nx = b.st[1];
;         if (nloc == 0u) { xcd_barrier_complete(bar, b.x, nloc, nx); b.st[0] = nloc; b.st[1] = nx; }
;         const unsigned old = xb_add(&bar[XB_XSUB(b.x)], 1u);
;         const unsigned gen = old / nloc;
;         if (old + 1u == (gen + 1u) * nloc) {
;             __builtin_amdgcn_fence(__ATOMIC_RELEASE, "agent");
;             asm volatile("s_waitcnt vmcnt(0)" ::: "memory");
;             const unsigned og = xb_add(&bar[XB_TOP], 1u);
;             const unsigned tg = og / nx;
;             if (og + 1u == (tg + 1u) * nx) xb_add(&bar[XB_TOPGEN], 1u);
;             else XB_SPIN(xb_ld(&bar[XB_TOPGEN]) == tg, bar);
;             __builtin_amdgcn_fence(__ATOMIC_ACQUIRE, "agent");
;             xb_add(&bar[XB_XGEN(b.x)], 1u);
;             asm volatile("s_waitcnt vmcnt(0)" ::: "memory");
;         } else {
;             XB_SPIN(xb_ld(&bar[XB_XGEN(b.x)]) == gen, bar);
;             __builtin_amdgcn_fence(__ATOMIC_ACQUIRE, "agent");
;             asm volatile("s_waitcnt vmcnt(0)" ::: "memory");
;         }
;     }
;     __syncthreads();
; }
.LBB0_1175:
	s_waitcnt vmcnt(0)
	s_barrier
	s_cmp_lg_u64 s[92:93], 0
	s_cbranch_scc1 .Lbw_p10
	v_readlane_b32 s98, v238, 40
	s_nop 3
	s_cmp_gt_u32 s98, 6
	s_cbranch_scc1 .Lbw_p10
	v_mbcnt_lo_u32_b32 v235, -1, 0
	v_mbcnt_hi_u32_b32 v235, -1, v235
	s_add_i32 s98, s98, -1
	s_lshl_b32 s98, s98, 6
	v_add_u32_e32 v235, s98, v235
	s_lshr_b32 s99, s20, 3
	s_mul_i32 s99, s99, 0x58000
	v_lshrrev_b32_e32 v236, 1, v235
	v_and_b32_e32 v235, 1, v235
	v_min_u32_e32 v236, 175, v236
	v_mul_u32_u24_e32 v236, 0x800, v236
	v_lshl_or_b32 v236, v235, 7, v236
	v_add_u32_e32 v236, s99, v236
	s_add_u32 s100, s30, 0x1200000
	s_addc_u32 s101, s31, 0
	global_load_dword v237, v236, s[100:101]
.Lbw_p10:
	s_and_saveexec_b64 s[6:7], s[92:93]
	v_readlane_b32 s68, v238, 10
	v_readlane_b32 s62, v238, 14
	v_readlane_b32 s69, v238, 11
	v_readlane_b32 s63, v238, 15
	s_cbranch_execz .LBB0_1227
	s_add_i32 s2, 0, 0x23fe0
	v_mov_b32_e32 v0, s2
	s_waitcnt vmcnt(0) expcnt(0) lgkmcnt(0)
	ds_read_b32 v2, v0
	s_add_i32 s2, 0, 0x23fe4
	v_mov_b32_e32 v0, s2
	ds_read_b32 v0, v0
	s_waitcnt lgkmcnt(1)
	v_cmp_ne_u32_e32 vcc, 0, v2
	s_cbranch_vccnz .LBB0_1191
	s_add_u32 s8, s30, 0x1000
	s_addc_u32 s9, s31, 0
	s_add_u32 s10, s30, 0x1100
	s_addc_u32 s11, s31, 0
	s_add_u32 s12, s30, 0x1200
	s_addc_u32 s13, s31, 0
	s_mul_i32 s2, s91, s85
	s_add_u32 s14, s30, 0x1300
	s_mul_i32 s2, s2, s90
	s_addc_u32 s15, s31, 0
	s_mov_b32 s16, 1
	v_mov_b32_e32 v16, 0
	s_branch .LBB0_1179

; __device__ __forceinline__ unsigned xb_ld(unsigned* p)              { return __hip_atomic_load(p, __ATOMIC_RELAXED, __HIP_MEMORY_SCOPE_AGENT); }
; __device__ __forceinline__ unsigned xb_add(unsigned* p, unsigned v) { return __hip_atomic_fetch_add(p, v, __ATOMIC_RELAXED, __HIP_MEMORY_SCOPE_AGENT); }
; #define XB_SPIN(cond, bar) do { unsigned _sp = 0; while (cond) { __builtin_amdgcn_s_sleep(1); \
;     if ((++_sp & 255u) == 0u) { if (xb_ld(&(bar)[XB_TMO])) break; if (_sp > XB_SPIN_CAP) { atomicAdd(&(bar)[XB_TMO], 1u); break; } } } } while (0)
; __device__ __forceinline__ void xcd_barrier(const XcdBarrier& b) {
;     asm volatile("s_waitcnt vmcnt(0)" ::: "memory");
;     __syncthreads();
;     if (threadIdx.x == 0) {
;         unsigned* bar = b.bar;
;         __builtin_amdgcn_s_waitcnt(0);
;         unsigned nloc = b.st[0], nx = b.st[1];
;         if (nloc == 0u) { xcd_barrier_complete(bar, b.x, nloc, nx); b.st[0] = nloc; b.st[1] = nx; }
;         const unsigned old = xb_add(&bar[XB_XSUB(b.x)], 1u);
;         const unsigned gen = old / nloc;
;         if (old + 1u == (gen + 1u) * nloc) {
;             __builtin_amdgcn_fence(__ATOMIC_RELEASE, "agent");
;             asm volatile("s_waitcnt vmcnt(0)" ::: "memory");
;             const unsigned og = xb_add(&bar[XB_TOP], 1u);
;             const unsigned tg = og / nx;
;             if (og + 1u == (tg + 1u) * nx) xb_add(&bar[XB_TOPGEN], 1u);
;             else XB_SPIN(xb_ld(&bar[XB_TOPGEN]) == tg, bar);
;             __builtin_amdgcn_fence(__ATOMIC_ACQUIRE, "agent");
;             xb_add(&bar[XB_XGEN(b.x)], 1u);
;             asm volatile("s_waitcnt vmcnt(0)" ::: "memory");
;         } else {
;             XB_SPIN(xb_ld(&bar[XB_XGEN(b.x)]) == gen, bar);
;             __builtin_amdgcn_fence(__ATOMIC_ACQUIRE, "agent");
;             asm volatile("s_waitcnt vmcnt(0)" ::: "memory");
;         }
;     }
;     __syncthreads();
; }
.LBB0_1243:
	s_waitcnt vmcnt(0)
	s_waitcnt vmcnt(0)
	s_barrier
	s_cmp_lg_u64 s[92:93], 0
	s_cbranch_scc1 .Lbw_p11
	v_readlane_b32 s98, v238, 40
	s_nop 3
	s_cmp_gt_u32 s98, 1
	s_cbranch_scc1 .Lbw_p11
	v_mbcnt_lo_u32_b32 v235, -1, 0
	v_mbcnt_hi_u32_b32 v235, -1, v235
	s_add_i32 s98, s98, -1
	s_lshl_b32 s98, s98, 6
	v_add_u32_e32 v235, s98, v235
	s_lshr_b32 s99, s20, 3
	s_mul_i32 s99, s99, 0x2c000
	v_lshrrev_b32_e32 v236, 1, v235
	v_and_b32_e32 v235, 1, v235
	v_min_u32_e32 v236, 31, v236
	v_mul_u32_u24_e32 v236, 0x1600, v236
	v_lshl_or_b32 v236, v235, 7, v236
	v_add_u32_e32 v236, s99, v236
	s_add_u32 s100, s30, 0x1d00000
	s_addc_u32 s101, s31, 0
	global_load_dword v237, v236, s[100:101]
.Lbw_p11:
	s_and_saveexec_b64 s[6:7], s[92:93]
	s_cbranch_execz .LBB0_1295
	s_add_i32 s2, 0, 0x23fe0
	v_mov_b32_e32 v0, s2
	s_waitcnt vmcnt(0) expcnt(0) lgkmcnt(0)
	ds_read_b32 v2, v0
	s_add_i32 s2, 0, 0x23fe4
	v_mov_b32_e32 v0, s2
	ds_read_b32 v0, v0
	s_waitcnt lgkmcnt(1)
	v_cmp_ne_u32_e32 vcc, 0, v2
	s_cbranch_vccnz .LBB0_1259
	s_add_u32 s8, s30, 0x1000
	s_addc_u32 s9, s31, 0
	s_add_u32 s10, s30, 0x1100
	s_addc_u32 s11, s31, 0
	s_add_u32 s12, s30, 0x1200
	s_addc_u32 s13, s31, 0
	s_mul_i32 s2, s91, s85
	s_add_u32 s14, s30, 0x1300
	s_mul_i32 s2, s2, s90
	s_addc_u32 s15, s31, 0
	s_mov_b32 s3, 1
	v_mov_b32_e32 v16, 0
	s_branch .LBB0_1247
